# v20 + the three GEMM k-loop heads aligned to 64 bytes (s_nop fill outside the loops)
# baseline (speedup 1.0000x reference)
.Lpj_peel_wj:
	s_waitcnt lgkmcnt(0)
	s_barrier
	s_setprio 1
	s_waitcnt lgkmcnt(0)
	v_mfma_f32_16x16x32_bf16 v[62:65], v[130:133], v[184:187], 0
	v_mfma_f32_16x16x32_bf16 v[58:61], v[138:141], v[184:187], 0
	v_mfma_f32_16x16x32_bf16 v[46:49], v[130:133], v[192:195], 0
	v_mfma_f32_16x16x32_bf16 v[42:45], v[138:141], v[192:195], 0
	v_mfma_f32_16x16x32_bf16 v[30:33], v[130:133], v[200:203], 0
	v_mfma_f32_16x16x32_bf16 v[26:29], v[138:141], v[200:203], 0
	v_mfma_f32_16x16x32_bf16 v[14:17], v[130:133], v[228:231], 0
	v_mfma_f32_16x16x32_bf16 v[10:13], v[138:141], v[228:231], 0
	v_mfma_f32_16x16x32_bf16 v[62:65], v[134:137], v[188:191], v[62:65]
	v_mfma_f32_16x16x32_bf16 v[58:61], v[142:145], v[188:191], v[58:61]
	v_mfma_f32_16x16x32_bf16 v[46:49], v[134:137], v[196:199], v[46:49]
	v_mfma_f32_16x16x32_bf16 v[42:45], v[142:145], v[196:199], v[42:45]
	v_mfma_f32_16x16x32_bf16 v[30:33], v[134:137], v[204:207], v[30:33]
	v_mfma_f32_16x16x32_bf16 v[26:29], v[142:145], v[204:207], v[26:29]
	v_mfma_f32_16x16x32_bf16 v[14:17], v[134:137], v[232:235], v[14:17]
	v_mfma_f32_16x16x32_bf16 v[10:13], v[142:145], v[232:235], v[10:13]
	s_setprio 0
	s_setprio 1
	v_mfma_f32_16x16x32_bf16 v[54:57], v[146:149], v[184:187], 0
	v_mfma_f32_16x16x32_bf16 v[50:53], v[176:179], v[184:187], 0
	v_mfma_f32_16x16x32_bf16 v[38:41], v[146:149], v[192:195], 0
	v_mfma_f32_16x16x32_bf16 v[34:37], v[176:179], v[192:195], 0
	v_mfma_f32_16x16x32_bf16 v[22:25], v[146:149], v[200:203], 0
	v_mfma_f32_16x16x32_bf16 v[18:21], v[176:179], v[200:203], 0
	v_mfma_f32_16x16x32_bf16 v[6:9], v[146:149], v[228:231], 0
	v_mfma_f32_16x16x32_bf16 v[2:5], v[176:179], v[228:231], 0
	v_mfma_f32_16x16x32_bf16 v[54:57], v[150:153], v[188:191], v[54:57]
	v_mfma_f32_16x16x32_bf16 v[50:53], v[180:183], v[188:191], v[50:53]
	v_mfma_f32_16x16x32_bf16 v[38:41], v[150:153], v[196:199], v[38:41]
	v_mfma_f32_16x16x32_bf16 v[34:37], v[180:183], v[196:199], v[34:37]
	v_mfma_f32_16x16x32_bf16 v[22:25], v[150:153], v[204:207], v[22:25]
	v_mfma_f32_16x16x32_bf16 v[18:21], v[180:183], v[204:207], v[18:21]
	v_mfma_f32_16x16x32_bf16 v[6:9], v[150:153], v[232:235], v[6:9]
	v_mfma_f32_16x16x32_bf16 v[2:5], v[180:183], v[232:235], v[2:5]
	s_setprio 0
	s_barrier
	s_add_i32 s56, 0, 0x18000
	s_add_i32 s57, 0, 0x1c000
	v_add_u32_e32 v142, s56, v224
	v_add_u32_e32 v164, s57, v224
	ds_read_b128 v[130:133], v142
	ds_read_b128 v[134:137], v142 offset:1024
	ds_read_b128 v[138:141], v142 offset:2048
	ds_read_b128 v[142:145], v142 offset:3072
	ds_read_b128 v[146:149], v164
	ds_read_b128 v[150:153], v164 offset:1024
	ds_read_b128 v[176:179], v164 offset:2048
	ds_read_b128 v[180:183], v164 offset:3072
	s_add_u32 s30, s30, 0x40000
	s_addc_u32 s31, s31, 0
	s_mov_b32 m0, s39
	v_lshl_add_u64 v[236:237], s[30:31], 0, v[154:155]
	ds_read_b128 v[184:187], v226 offset:32768
	ds_read_b128 v[188:191], v226 offset:33792
	ds_read_b128 v[192:195], v226 offset:34816
	ds_read_b128 v[196:199], v226 offset:35840
	ds_read_b128 v[200:203], v226 offset:36864
	ds_read_b128 v[204:207], v226 offset:37888
	ds_read_b128 v[228:231], v226 offset:38912
	ds_read_b128 v[232:235], v226 offset:39936
	global_load_lds_dwordx4 v[236:237], off
	v_lshl_add_u64 v[236:237], s[30:31], 0, v[156:157]
	s_mov_b32 m0, s40
	s_nop 0
	global_load_lds_dwordx4 v[236:237], off
	s_waitcnt vmcnt(8)
	s_waitcnt lgkmcnt(0)
	s_barrier
	s_setprio 1
	s_waitcnt lgkmcnt(0)
	v_mfma_f32_16x16x32_bf16 v[126:129], v[130:133], v[184:187], v[126:129]
	v_mfma_f32_16x16x32_bf16 v[122:125], v[138:141], v[184:187], v[122:125]
	v_mfma_f32_16x16x32_bf16 v[110:113], v[130:133], v[192:195], v[110:113]
	v_mfma_f32_16x16x32_bf16 v[106:109], v[138:141], v[192:195], v[106:109]
	v_mfma_f32_16x16x32_bf16 v[94:97], v[130:133], v[200:203], v[94:97]
	v_mfma_f32_16x16x32_bf16 v[90:93], v[138:141], v[200:203], v[90:93]
	v_mfma_f32_16x16x32_bf16 v[78:81], v[130:133], v[228:231], v[78:81]
	v_mfma_f32_16x16x32_bf16 v[74:77], v[138:141], v[228:231], v[74:77]
	v_mfma_f32_16x16x32_bf16 v[126:129], v[134:137], v[188:191], v[126:129]
	v_mfma_f32_16x16x32_bf16 v[122:125], v[142:145], v[188:191], v[122:125]
	v_mfma_f32_16x16x32_bf16 v[110:113], v[134:137], v[196:199], v[110:113]
	v_mfma_f32_16x16x32_bf16 v[106:109], v[142:145], v[196:199], v[106:109]
	v_mfma_f32_16x16x32_bf16 v[94:97], v[134:137], v[204:207], v[94:97]
	v_mfma_f32_16x16x32_bf16 v[90:93], v[142:145], v[204:207], v[90:93]
	v_mfma_f32_16x16x32_bf16 v[78:81], v[134:137], v[232:235], v[78:81]
	v_mfma_f32_16x16x32_bf16 v[74:77], v[142:145], v[232:235], v[74:77]
	s_setprio 0
	s_setprio 1
	v_mfma_f32_16x16x32_bf16 v[118:121], v[146:149], v[184:187], v[118:121]
	v_mfma_f32_16x16x32_bf16 v[114:117], v[176:179], v[184:187], v[114:117]
	v_mfma_f32_16x16x32_bf16 v[102:105], v[146:149], v[192:195], v[102:105]
	v_mfma_f32_16x16x32_bf16 v[98:101], v[176:179], v[192:195], v[98:101]
	v_mfma_f32_16x16x32_bf16 v[86:89], v[146:149], v[200:203], v[86:89]
	v_mfma_f32_16x16x32_bf16 v[82:85], v[176:179], v[200:203], v[82:85]
	v_mfma_f32_16x16x32_bf16 v[70:73], v[146:149], v[228:231], v[70:73]
	v_mfma_f32_16x16x32_bf16 v[66:69], v[176:179], v[228:231], v[66:69]
	v_mfma_f32_16x16x32_bf16 v[118:121], v[150:153], v[188:191], v[118:121]
	v_mfma_f32_16x16x32_bf16 v[114:117], v[180:183], v[188:191], v[114:117]
	v_mfma_f32_16x16x32_bf16 v[102:105], v[150:153], v[196:199], v[102:105]
	v_mfma_f32_16x16x32_bf16 v[98:101], v[180:183], v[196:199], v[98:101]
	v_mfma_f32_16x16x32_bf16 v[86:89], v[150:153], v[204:207], v[86:89]
	v_mfma_f32_16x16x32_bf16 v[82:85], v[180:183], v[204:207], v[82:85]
	v_mfma_f32_16x16x32_bf16 v[70:73], v[150:153], v[232:235], v[70:73]
	v_mfma_f32_16x16x32_bf16 v[66:69], v[180:183], v[232:235], v[66:69]
	s_setprio 0
	s_barrier
	s_add_i32 s30, s56, s36
	v_lshl_add_u64 v[162:163], v[162:163], 0, s[86:87]
	s_mov_b32 m0, s30
	ds_read_b128 v[184:187], v226 offset:49152
	ds_read_b128 v[188:191], v226 offset:50176
	ds_read_b128 v[192:195], v226 offset:51200
	ds_read_b128 v[196:199], v226 offset:52224
	ds_read_b128 v[200:203], v226 offset:53248
	ds_read_b128 v[204:207], v226 offset:54272
	ds_read_b128 v[228:231], v226 offset:55296
	ds_read_b128 v[232:235], v226 offset:56320
	global_load_lds_dwordx4 v[162:163], off
	s_add_i32 m0, s30, 0x2000
	s_add_u32 s28, s28, 0x40080
	v_lshl_add_u64 v[162:163], v[208:209], 0, s[86:87]
	s_addc_u32 s29, s29, 0
	s_add_i32 s30, s57, s36
	global_load_lds_dwordx4 v[162:163], off
	v_lshl_add_u64 v[162:163], s[28:29], 0, v[0:1]
	s_mov_b32 m0, s30
	s_nop 0
	global_load_lds_dwordx4 v[162:163], off
	v_lshl_add_u64 v[162:163], s[28:29], 0, v[158:159]
	s_add_i32 m0, s30, 0x2000
	s_nop 0
	global_load_lds_dwordx4 v[162:163], off
	v_lshl_add_u64 v[162:163], v[214:215], 0, s[86:87]
	s_mov_b32 m0, s44
	s_nop 0
	global_load_lds_dwordx4 v[162:163], off
	v_lshl_add_u64 v[162:163], v[216:217], 0, s[86:87]
	s_mov_b32 m0, s45
	s_nop 0
	global_load_lds_dwordx4 v[162:163], off
	s_waitcnt vmcnt(8)
	s_waitcnt lgkmcnt(0)
	s_barrier
	s_setprio 1
	s_waitcnt lgkmcnt(0)
	v_mfma_f32_16x16x32_bf16 v[62:65], v[130:133], v[184:187], v[62:65]
	v_mfma_f32_16x16x32_bf16 v[58:61], v[138:141], v[184:187], v[58:61]
	v_mfma_f32_16x16x32_bf16 v[46:49], v[130:133], v[192:195], v[46:49]
	v_mfma_f32_16x16x32_bf16 v[42:45], v[138:141], v[192:195], v[42:45]
	v_mfma_f32_16x16x32_bf16 v[30:33], v[130:133], v[200:203], v[30:33]
	v_mfma_f32_16x16x32_bf16 v[26:29], v[138:141], v[200:203], v[26:29]
	v_mfma_f32_16x16x32_bf16 v[14:17], v[130:133], v[228:231], v[14:17]
	v_mfma_f32_16x16x32_bf16 v[10:13], v[138:141], v[228:231], v[10:13]
	v_mfma_f32_16x16x32_bf16 v[62:65], v[134:137], v[188:191], v[62:65]
	v_mfma_f32_16x16x32_bf16 v[58:61], v[142:145], v[188:191], v[58:61]
	v_mfma_f32_16x16x32_bf16 v[46:49], v[134:137], v[196:199], v[46:49]
	v_mfma_f32_16x16x32_bf16 v[42:45], v[142:145], v[196:199], v[42:45]
	v_mfma_f32_16x16x32_bf16 v[30:33], v[134:137], v[204:207], v[30:33]
	v_mfma_f32_16x16x32_bf16 v[26:29], v[142:145], v[204:207], v[26:29]
	v_mfma_f32_16x16x32_bf16 v[14:17], v[134:137], v[232:235], v[14:17]
	v_mfma_f32_16x16x32_bf16 v[10:13], v[142:145], v[232:235], v[10:13]
	s_setprio 0
	s_setprio 1
	v_mfma_f32_16x16x32_bf16 v[54:57], v[146:149], v[184:187], v[54:57]
	v_mfma_f32_16x16x32_bf16 v[50:53], v[176:179], v[184:187], v[50:53]
	v_mfma_f32_16x16x32_bf16 v[38:41], v[146:149], v[192:195], v[38:41]
	v_mfma_f32_16x16x32_bf16 v[34:37], v[176:179], v[192:195], v[34:37]
	v_mfma_f32_16x16x32_bf16 v[22:25], v[146:149], v[200:203], v[22:25]
	v_mfma_f32_16x16x32_bf16 v[18:21], v[176:179], v[200:203], v[18:21]
	v_mfma_f32_16x16x32_bf16 v[6:9], v[146:149], v[228:231], v[6:9]
	v_mfma_f32_16x16x32_bf16 v[2:5], v[176:179], v[228:231], v[2:5]
	v_mfma_f32_16x16x32_bf16 v[54:57], v[150:153], v[188:191], v[54:57]
	v_mfma_f32_16x16x32_bf16 v[50:53], v[180:183], v[188:191], v[50:53]
	v_mfma_f32_16x16x32_bf16 v[38:41], v[150:153], v[196:199], v[38:41]
	v_mfma_f32_16x16x32_bf16 v[34:37], v[180:183], v[196:199], v[34:37]
	v_mfma_f32_16x16x32_bf16 v[22:25], v[150:153], v[204:207], v[22:25]
	v_mfma_f32_16x16x32_bf16 v[18:21], v[180:183], v[204:207], v[18:21]
	v_mfma_f32_16x16x32_bf16 v[6:9], v[150:153], v[232:235], v[6:9]
	v_mfma_f32_16x16x32_bf16 v[2:5], v[180:183], v[232:235], v[2:5]
	s_setprio 0
	s_barrier
	s_add_i32 s55, s55, 2
	s_add_u32 s8, s8, 0x100
	s_addc_u32 s9, s9, 0
	s_add_u32 s53, s53, 0x100
	s_addc_u32 s54, s54, 0
	s_cmp_gt_u32 s55, 13
	s_cbranch_scc0 .LBB0_809
	.p2alignl 6, 3212836864

.Lrs_peel_wj:
	s_waitcnt lgkmcnt(0)
	s_barrier
	s_setprio 1
	s_waitcnt lgkmcnt(0)
	v_mfma_f32_16x16x32_bf16 v[62:65], v[122:125], v[182:185], 0
	v_mfma_f32_16x16x32_bf16 v[58:61], v[138:141], v[182:185], 0
	v_mfma_f32_16x16x32_bf16 v[46:49], v[122:125], v[190:193], 0
	v_mfma_f32_16x16x32_bf16 v[42:45], v[138:141], v[190:193], 0
	v_mfma_f32_16x16x32_bf16 v[30:33], v[122:125], v[204:207], 0
	v_mfma_f32_16x16x32_bf16 v[26:29], v[138:141], v[204:207], 0
	v_mfma_f32_16x16x32_bf16 v[14:17], v[122:125], v[228:231], 0
	v_mfma_f32_16x16x32_bf16 v[10:13], v[138:141], v[228:231], 0
	v_mfma_f32_16x16x32_bf16 v[62:65], v[134:137], v[186:189], v[62:65]
	v_mfma_f32_16x16x32_bf16 v[58:61], v[142:145], v[186:189], v[58:61]
	v_mfma_f32_16x16x32_bf16 v[46:49], v[134:137], v[200:203], v[46:49]
	v_mfma_f32_16x16x32_bf16 v[42:45], v[142:145], v[200:203], v[42:45]
	v_mfma_f32_16x16x32_bf16 v[30:33], v[134:137], v[224:227], v[30:33]
	v_mfma_f32_16x16x32_bf16 v[26:29], v[142:145], v[224:227], v[26:29]
	v_mfma_f32_16x16x32_bf16 v[14:17], v[134:137], v[232:235], v[14:17]
	v_mfma_f32_16x16x32_bf16 v[10:13], v[142:145], v[232:235], v[10:13]
	s_setprio 0
	s_setprio 1
	v_mfma_f32_16x16x32_bf16 v[54:57], v[146:149], v[182:185], 0
	v_mfma_f32_16x16x32_bf16 v[50:53], v[154:157], v[182:185], 0
	v_mfma_f32_16x16x32_bf16 v[38:41], v[146:149], v[190:193], 0
	v_mfma_f32_16x16x32_bf16 v[34:37], v[154:157], v[190:193], 0
	v_mfma_f32_16x16x32_bf16 v[22:25], v[146:149], v[204:207], 0
	v_mfma_f32_16x16x32_bf16 v[18:21], v[154:157], v[204:207], 0
	v_mfma_f32_16x16x32_bf16 v[6:9], v[146:149], v[228:231], 0
	v_mfma_f32_16x16x32_bf16 v[2:5], v[154:157], v[228:231], 0
	v_mfma_f32_16x16x32_bf16 v[54:57], v[150:153], v[186:189], v[54:57]
	v_mfma_f32_16x16x32_bf16 v[50:53], v[178:181], v[186:189], v[50:53]
	v_mfma_f32_16x16x32_bf16 v[38:41], v[150:153], v[200:203], v[38:41]
	v_mfma_f32_16x16x32_bf16 v[34:37], v[178:181], v[200:203], v[34:37]
	v_mfma_f32_16x16x32_bf16 v[22:25], v[150:153], v[224:227], v[22:25]
	v_mfma_f32_16x16x32_bf16 v[18:21], v[178:181], v[224:227], v[18:21]
	v_mfma_f32_16x16x32_bf16 v[6:9], v[150:153], v[232:235], v[6:9]
	v_mfma_f32_16x16x32_bf16 v[2:5], v[178:181], v[232:235], v[2:5]
	s_setprio 0
	s_barrier
	s_add_i32 s48, 0, 0x18000
	s_add_i32 s49, 0, 0x1c000
	v_add_u32_e32 v142, s48, v197
	v_add_u32_e32 v164, s49, v197
	ds_read_b128 v[122:125], v142
	ds_read_b128 v[134:137], v142 offset:1024
	ds_read_b128 v[138:141], v142 offset:2048
	ds_read_b128 v[142:145], v142 offset:3072
	ds_read_b128 v[146:149], v164
	ds_read_b128 v[150:153], v164 offset:1024
	ds_read_b128 v[154:157], v164 offset:2048
	ds_read_b128 v[178:181], v164 offset:3072
	s_add_u32 s24, s24, s10
	s_addc_u32 s25, s25, 0
	s_mov_b32 m0, s35
	v_lshl_add_u64 v[238:239], s[24:25], 0, v[172:173]
	ds_read_b128 v[182:185], v199 offset:32768
	ds_read_b128 v[186:189], v199 offset:33792
	ds_read_b128 v[190:193], v199 offset:34816
	ds_read_b128 v[200:203], v199 offset:35840
	ds_read_b128 v[204:207], v199 offset:36864
	ds_read_b128 v[224:227], v199 offset:37888
	ds_read_b128 v[228:231], v199 offset:38912
	ds_read_b128 v[232:235], v199 offset:39936
	global_load_lds_dwordx4 v[238:239], off
	v_lshl_add_u64 v[238:239], s[24:25], 0, v[170:171]
	s_mov_b32 m0, s36
	s_nop 0
	global_load_lds_dwordx4 v[238:239], off
	s_waitcnt vmcnt(8)
	s_waitcnt lgkmcnt(0)
	s_barrier
	s_setprio 1
	s_waitcnt lgkmcnt(0)
	v_mfma_f32_16x16x32_bf16 v[130:133], v[122:125], v[182:185], v[130:133]
	v_mfma_f32_16x16x32_bf16 v[126:129], v[138:141], v[182:185], v[126:129]
	v_mfma_f32_16x16x32_bf16 v[110:113], v[122:125], v[190:193], v[110:113]
	v_mfma_f32_16x16x32_bf16 v[106:109], v[138:141], v[190:193], v[106:109]
	v_mfma_f32_16x16x32_bf16 v[94:97], v[122:125], v[204:207], v[94:97]
	v_mfma_f32_16x16x32_bf16 v[90:93], v[138:141], v[204:207], v[90:93]
	v_mfma_f32_16x16x32_bf16 v[78:81], v[122:125], v[228:231], v[78:81]
	v_mfma_f32_16x16x32_bf16 v[74:77], v[138:141], v[228:231], v[74:77]
	v_mfma_f32_16x16x32_bf16 v[130:133], v[134:137], v[186:189], v[130:133]
	v_mfma_f32_16x16x32_bf16 v[126:129], v[142:145], v[186:189], v[126:129]
	v_mfma_f32_16x16x32_bf16 v[110:113], v[134:137], v[200:203], v[110:113]
	v_mfma_f32_16x16x32_bf16 v[106:109], v[142:145], v[200:203], v[106:109]
	v_mfma_f32_16x16x32_bf16 v[94:97], v[134:137], v[224:227], v[94:97]
	v_mfma_f32_16x16x32_bf16 v[90:93], v[142:145], v[224:227], v[90:93]
	v_mfma_f32_16x16x32_bf16 v[78:81], v[134:137], v[232:235], v[78:81]
	v_mfma_f32_16x16x32_bf16 v[74:77], v[142:145], v[232:235], v[74:77]
	s_setprio 0
	s_setprio 1
	v_mfma_f32_16x16x32_bf16 v[118:121], v[146:149], v[182:185], v[118:121]
	v_mfma_f32_16x16x32_bf16 v[114:117], v[154:157], v[182:185], v[114:117]
	v_mfma_f32_16x16x32_bf16 v[102:105], v[146:149], v[190:193], v[102:105]
	v_mfma_f32_16x16x32_bf16 v[98:101], v[154:157], v[190:193], v[98:101]
	v_mfma_f32_16x16x32_bf16 v[86:89], v[146:149], v[204:207], v[86:89]
	v_mfma_f32_16x16x32_bf16 v[82:85], v[154:157], v[204:207], v[82:85]
	v_mfma_f32_16x16x32_bf16 v[70:73], v[146:149], v[228:231], v[70:73]
	v_mfma_f32_16x16x32_bf16 v[66:69], v[154:157], v[228:231], v[66:69]
	v_mfma_f32_16x16x32_bf16 v[118:121], v[150:153], v[186:189], v[118:121]
	v_mfma_f32_16x16x32_bf16 v[114:117], v[178:181], v[186:189], v[114:117]
	v_mfma_f32_16x16x32_bf16 v[102:105], v[150:153], v[200:203], v[102:105]
	v_mfma_f32_16x16x32_bf16 v[98:101], v[178:181], v[200:203], v[98:101]
	v_mfma_f32_16x16x32_bf16 v[86:89], v[150:153], v[224:227], v[86:89]
	v_mfma_f32_16x16x32_bf16 v[82:85], v[178:181], v[224:227], v[82:85]
	v_mfma_f32_16x16x32_bf16 v[70:73], v[150:153], v[232:235], v[70:73]
	v_mfma_f32_16x16x32_bf16 v[66:69], v[178:181], v[232:235], v[66:69]
	s_setprio 0
	s_barrier
	s_add_i32 s24, s48, s30
	v_lshl_add_u64 v[162:163], v[162:163], 0, s[86:87]
	s_mov_b32 m0, s24
	ds_read_b128 v[182:185], v199 offset:49152
	ds_read_b128 v[186:189], v199 offset:50176
	ds_read_b128 v[190:193], v199 offset:51200
	ds_read_b128 v[200:203], v199 offset:52224
	ds_read_b128 v[204:207], v199 offset:53248
	ds_read_b128 v[224:227], v199 offset:54272
	ds_read_b128 v[228:231], v199 offset:55296
	ds_read_b128 v[232:235], v199 offset:56320
	global_load_lds_dwordx4 v[162:163], off
	v_lshl_add_u64 v[162:163], v[194:195], 0, s[86:87]
	s_add_i32 m0, s24, 0x2000
	s_add_i32 s24, s49, s30
	global_load_lds_dwordx4 v[162:163], off
	v_lshl_add_u64 v[162:163], v[208:209], 0, s[86:87]
	s_mov_b32 m0, s24
	s_nop 0
	global_load_lds_dwordx4 v[162:163], off
	v_lshl_add_u64 v[162:163], v[214:215], 0, s[86:87]
	s_add_i32 m0, s24, 0x2000
	s_nop 0
	global_load_lds_dwordx4 v[162:163], off
	v_lshl_add_u64 v[162:163], v[216:217], 0, s[86:87]
	s_mov_b32 m0, s37
	s_nop 0
	global_load_lds_dwordx4 v[162:163], off
	v_lshl_add_u64 v[162:163], v[236:237], 0, s[86:87]
	s_mov_b32 m0, s38
	s_nop 0
	global_load_lds_dwordx4 v[162:163], off
	s_waitcnt vmcnt(8)
	s_waitcnt lgkmcnt(0)
	s_barrier
	s_setprio 1
	s_waitcnt lgkmcnt(0)
	v_mfma_f32_16x16x32_bf16 v[62:65], v[122:125], v[182:185], v[62:65]
	v_mfma_f32_16x16x32_bf16 v[58:61], v[138:141], v[182:185], v[58:61]
	v_mfma_f32_16x16x32_bf16 v[46:49], v[122:125], v[190:193], v[46:49]
	v_mfma_f32_16x16x32_bf16 v[42:45], v[138:141], v[190:193], v[42:45]
	v_mfma_f32_16x16x32_bf16 v[30:33], v[122:125], v[204:207], v[30:33]
	v_mfma_f32_16x16x32_bf16 v[26:29], v[138:141], v[204:207], v[26:29]
	v_mfma_f32_16x16x32_bf16 v[14:17], v[122:125], v[228:231], v[14:17]
	v_mfma_f32_16x16x32_bf16 v[10:13], v[138:141], v[228:231], v[10:13]
	v_mfma_f32_16x16x32_bf16 v[62:65], v[134:137], v[186:189], v[62:65]
	v_mfma_f32_16x16x32_bf16 v[58:61], v[142:145], v[186:189], v[58:61]
	v_mfma_f32_16x16x32_bf16 v[46:49], v[134:137], v[200:203], v[46:49]
	v_mfma_f32_16x16x32_bf16 v[42:45], v[142:145], v[200:203], v[42:45]
	v_mfma_f32_16x16x32_bf16 v[30:33], v[134:137], v[224:227], v[30:33]
	v_mfma_f32_16x16x32_bf16 v[26:29], v[142:145], v[224:227], v[26:29]
	v_mfma_f32_16x16x32_bf16 v[14:17], v[134:137], v[232:235], v[14:17]
	v_mfma_f32_16x16x32_bf16 v[10:13], v[142:145], v[232:235], v[10:13]
	s_setprio 0
	s_setprio 1
	v_mfma_f32_16x16x32_bf16 v[54:57], v[146:149], v[182:185], v[54:57]
	v_mfma_f32_16x16x32_bf16 v[50:53], v[154:157], v[182:185], v[50:53]
	v_mfma_f32_16x16x32_bf16 v[38:41], v[146:149], v[190:193], v[38:41]
	v_mfma_f32_16x16x32_bf16 v[34:37], v[154:157], v[190:193], v[34:37]
	v_mfma_f32_16x16x32_bf16 v[22:25], v[146:149], v[204:207], v[22:25]
	v_mfma_f32_16x16x32_bf16 v[18:21], v[154:157], v[204:207], v[18:21]
	v_mfma_f32_16x16x32_bf16 v[6:9], v[146:149], v[228:231], v[6:9]
	v_mfma_f32_16x16x32_bf16 v[2:5], v[154:157], v[228:231], v[2:5]
	v_mfma_f32_16x16x32_bf16 v[54:57], v[150:153], v[186:189], v[54:57]
	v_mfma_f32_16x16x32_bf16 v[50:53], v[178:181], v[186:189], v[50:53]
	v_mfma_f32_16x16x32_bf16 v[38:41], v[150:153], v[200:203], v[38:41]
	v_mfma_f32_16x16x32_bf16 v[34:37], v[178:181], v[200:203], v[34:37]
	v_mfma_f32_16x16x32_bf16 v[22:25], v[150:153], v[224:227], v[22:25]
	v_mfma_f32_16x16x32_bf16 v[18:21], v[178:181], v[224:227], v[18:21]
	v_mfma_f32_16x16x32_bf16 v[6:9], v[150:153], v[232:235], v[6:9]
	v_mfma_f32_16x16x32_bf16 v[2:5], v[178:181], v[232:235], v[2:5]
	s_setprio 0
	s_barrier
	s_add_u32 s6, s6, 0x100
	s_addc_u32 s7, s7, 0
	s_add_u32 s26, s26, 0x100
	s_addc_u32 s27, s27, 0
	s_cmp_ge_u32 s47, s40
	s_mov_b32 s24, s47
	s_cbranch_scc0 .LBB0_1344
	.p2alignl 6, 3212836864

.Lgu_peel_wj:
	s_waitcnt lgkmcnt(0)
	s_barrier
	s_setprio 1
	s_waitcnt lgkmcnt(0)
	v_mfma_f32_16x16x32_bf16 v[62:65], v[130:133], v[182:185], 0
	v_mfma_f32_16x16x32_bf16 v[54:57], v[138:141], v[182:185], 0
	v_mfma_f32_16x16x32_bf16 v[46:49], v[130:133], v[200:203], 0
	v_mfma_f32_16x16x32_bf16 v[38:41], v[138:141], v[200:203], 0
	v_mfma_f32_16x16x32_bf16 v[30:33], v[130:133], v[220:223], 0
	v_mfma_f32_16x16x32_bf16 v[22:25], v[138:141], v[220:223], 0
	v_mfma_f32_16x16x32_bf16 v[14:17], v[130:133], v[228:231], 0
	v_mfma_f32_16x16x32_bf16 v[6:9], v[138:141], v[228:231], 0
	v_mfma_f32_16x16x32_bf16 v[62:65], v[134:137], v[186:189], v[62:65]
	v_mfma_f32_16x16x32_bf16 v[54:57], v[142:145], v[186:189], v[54:57]
	v_mfma_f32_16x16x32_bf16 v[46:49], v[134:137], v[204:207], v[46:49]
	v_mfma_f32_16x16x32_bf16 v[38:41], v[142:145], v[204:207], v[38:41]
	v_mfma_f32_16x16x32_bf16 v[30:33], v[134:137], v[224:227], v[30:33]
	v_mfma_f32_16x16x32_bf16 v[22:25], v[142:145], v[224:227], v[22:25]
	v_mfma_f32_16x16x32_bf16 v[14:17], v[134:137], v[232:235], v[14:17]
	v_mfma_f32_16x16x32_bf16 v[6:9], v[142:145], v[232:235], v[6:9]
	s_setprio 0
	s_setprio 1
	v_mfma_f32_16x16x32_bf16 v[58:61], v[146:149], v[182:185], 0
	v_mfma_f32_16x16x32_bf16 v[50:53], v[174:177], v[182:185], 0
	v_mfma_f32_16x16x32_bf16 v[42:45], v[146:149], v[200:203], 0
	v_mfma_f32_16x16x32_bf16 v[34:37], v[174:177], v[200:203], 0
	v_mfma_f32_16x16x32_bf16 v[26:29], v[146:149], v[220:223], 0
	v_mfma_f32_16x16x32_bf16 v[18:21], v[174:177], v[220:223], 0
	v_mfma_f32_16x16x32_bf16 v[10:13], v[146:149], v[228:231], 0
	v_mfma_f32_16x16x32_bf16 v[2:5], v[174:177], v[228:231], 0
	v_mfma_f32_16x16x32_bf16 v[58:61], v[150:153], v[186:189], v[58:61]
	v_mfma_f32_16x16x32_bf16 v[50:53], v[178:181], v[186:189], v[50:53]
	v_mfma_f32_16x16x32_bf16 v[42:45], v[150:153], v[204:207], v[42:45]
	v_mfma_f32_16x16x32_bf16 v[34:37], v[178:181], v[204:207], v[34:37]
	v_mfma_f32_16x16x32_bf16 v[26:29], v[150:153], v[224:227], v[26:29]
	v_mfma_f32_16x16x32_bf16 v[18:21], v[178:181], v[224:227], v[18:21]
	v_mfma_f32_16x16x32_bf16 v[10:13], v[150:153], v[232:235], v[10:13]
	v_mfma_f32_16x16x32_bf16 v[2:5], v[178:181], v[232:235], v[2:5]
	s_setprio 0
	s_barrier
	s_add_i32 s42, 0, 0x18000
	s_add_i32 s43, 0, 0x1c000
	v_add_u32_e32 v142, s42, v195
	v_add_u32_e32 v164, s43, v195
	ds_read_b128 v[130:133], v142
	ds_read_b128 v[134:137], v142 offset:1024
	ds_read_b128 v[138:141], v142 offset:2048
	ds_read_b128 v[142:145], v142 offset:3072
	ds_read_b128 v[146:149], v164
	ds_read_b128 v[150:153], v164 offset:1024
	ds_read_b128 v[174:177], v164 offset:2048
	ds_read_b128 v[178:181], v164 offset:3072
	s_add_u32 s18, s18, 0x40000
	s_addc_u32 s19, s19, 0
	s_mov_b32 m0, s27
	v_lshl_add_u64 v[214:215], s[18:19], 0, v[158:159]
	ds_read_b128 v[182:185], v199 offset:32768
	ds_read_b128 v[186:189], v199 offset:33792
	ds_read_b128 v[200:203], v199 offset:34816
	ds_read_b128 v[204:207], v199 offset:35840
	ds_read_b128 v[220:223], v199 offset:36864
	ds_read_b128 v[224:227], v199 offset:37888
	ds_read_b128 v[228:231], v199 offset:38912
	ds_read_b128 v[232:235], v199 offset:39936
	global_load_lds_dwordx4 v[214:215], off
	v_lshl_add_u64 v[214:215], s[18:19], 0, v[156:157]
	s_mov_b32 m0, s28
	s_nop 0
	global_load_lds_dwordx4 v[214:215], off
	s_waitcnt vmcnt(8)
	s_waitcnt lgkmcnt(0)
	s_barrier
	s_setprio 1
	s_waitcnt lgkmcnt(0)
	v_mfma_f32_16x16x32_bf16 v[126:129], v[130:133], v[182:185], v[126:129]
	v_mfma_f32_16x16x32_bf16 v[118:121], v[138:141], v[182:185], v[118:121]
	v_mfma_f32_16x16x32_bf16 v[110:113], v[130:133], v[200:203], v[110:113]
	v_mfma_f32_16x16x32_bf16 v[102:105], v[138:141], v[200:203], v[102:105]
	v_mfma_f32_16x16x32_bf16 v[94:97], v[130:133], v[220:223], v[94:97]
	v_mfma_f32_16x16x32_bf16 v[86:89], v[138:141], v[220:223], v[86:89]
	v_mfma_f32_16x16x32_bf16 v[78:81], v[130:133], v[228:231], v[78:81]
	v_mfma_f32_16x16x32_bf16 v[70:73], v[138:141], v[228:231], v[70:73]
	v_mfma_f32_16x16x32_bf16 v[126:129], v[134:137], v[186:189], v[126:129]
	v_mfma_f32_16x16x32_bf16 v[118:121], v[142:145], v[186:189], v[118:121]
	v_mfma_f32_16x16x32_bf16 v[110:113], v[134:137], v[204:207], v[110:113]
	v_mfma_f32_16x16x32_bf16 v[102:105], v[142:145], v[204:207], v[102:105]
	v_mfma_f32_16x16x32_bf16 v[94:97], v[134:137], v[224:227], v[94:97]
	v_mfma_f32_16x16x32_bf16 v[86:89], v[142:145], v[224:227], v[86:89]
	v_mfma_f32_16x16x32_bf16 v[78:81], v[134:137], v[232:235], v[78:81]
	v_mfma_f32_16x16x32_bf16 v[70:73], v[142:145], v[232:235], v[70:73]
	s_setprio 0
	s_setprio 1
	v_mfma_f32_16x16x32_bf16 v[122:125], v[146:149], v[182:185], v[122:125]
	v_mfma_f32_16x16x32_bf16 v[114:117], v[174:177], v[182:185], v[114:117]
	v_mfma_f32_16x16x32_bf16 v[106:109], v[146:149], v[200:203], v[106:109]
	v_mfma_f32_16x16x32_bf16 v[98:101], v[174:177], v[200:203], v[98:101]
	v_mfma_f32_16x16x32_bf16 v[90:93], v[146:149], v[220:223], v[90:93]
	v_mfma_f32_16x16x32_bf16 v[82:85], v[174:177], v[220:223], v[82:85]
	v_mfma_f32_16x16x32_bf16 v[74:77], v[146:149], v[228:231], v[74:77]
	v_mfma_f32_16x16x32_bf16 v[66:69], v[174:177], v[228:231], v[66:69]
	v_mfma_f32_16x16x32_bf16 v[122:125], v[150:153], v[186:189], v[122:125]
	v_mfma_f32_16x16x32_bf16 v[114:117], v[178:181], v[186:189], v[114:117]
	v_mfma_f32_16x16x32_bf16 v[106:109], v[150:153], v[204:207], v[106:109]
	v_mfma_f32_16x16x32_bf16 v[98:101], v[178:181], v[204:207], v[98:101]
	v_mfma_f32_16x16x32_bf16 v[90:93], v[150:153], v[224:227], v[90:93]
	v_mfma_f32_16x16x32_bf16 v[82:85], v[178:181], v[224:227], v[82:85]
	v_mfma_f32_16x16x32_bf16 v[74:77], v[150:153], v[232:235], v[74:77]
	v_mfma_f32_16x16x32_bf16 v[66:69], v[178:181], v[232:235], v[66:69]
	s_setprio 0
	s_barrier
	s_add_i32 s18, s42, s22
	v_lshl_add_u64 v[162:163], v[162:163], 0, s[86:87]
	s_mov_b32 m0, s18
	ds_read_b128 v[182:185], v199 offset:49152
	ds_read_b128 v[186:189], v199 offset:50176
	ds_read_b128 v[200:203], v199 offset:51200
	ds_read_b128 v[204:207], v199 offset:52224
	ds_read_b128 v[220:223], v199 offset:53248
	ds_read_b128 v[224:227], v199 offset:54272
	ds_read_b128 v[228:231], v199 offset:55296
	ds_read_b128 v[232:235], v199 offset:56320
	global_load_lds_dwordx4 v[162:163], off
	s_add_i32 m0, s18, 0x2000
	s_add_u32 s16, s16, 0x40080
	v_lshl_add_u64 v[162:163], v[190:191], 0, s[86:87]
	s_addc_u32 s17, s17, 0
	s_add_i32 s18, s43, s22
	global_load_lds_dwordx4 v[162:163], off
	v_lshl_add_u64 v[162:163], s[16:17], 0, v[0:1]
	s_mov_b32 m0, s18
	s_nop 0
	global_load_lds_dwordx4 v[162:163], off
	v_lshl_add_u64 v[162:163], s[16:17], 0, v[154:155]
	s_add_i32 m0, s18, 0x2000
	s_nop 0
	global_load_lds_dwordx4 v[162:163], off
	v_lshl_add_u64 v[162:163], v[196:197], 0, s[86:87]
	s_mov_b32 m0, s29
	s_nop 0
	global_load_lds_dwordx4 v[162:163], off
	v_lshl_add_u64 v[162:163], v[208:209], 0, s[86:87]
	s_mov_b32 m0, s30
	s_nop 0
	global_load_lds_dwordx4 v[162:163], off
	s_waitcnt vmcnt(8)
	s_waitcnt lgkmcnt(0)
	s_barrier
	s_setprio 1
	s_waitcnt lgkmcnt(0)
	v_mfma_f32_16x16x32_bf16 v[62:65], v[130:133], v[182:185], v[62:65]
	v_mfma_f32_16x16x32_bf16 v[54:57], v[138:141], v[182:185], v[54:57]
	v_mfma_f32_16x16x32_bf16 v[46:49], v[130:133], v[200:203], v[46:49]
	v_mfma_f32_16x16x32_bf16 v[38:41], v[138:141], v[200:203], v[38:41]
	v_mfma_f32_16x16x32_bf16 v[30:33], v[130:133], v[220:223], v[30:33]
	v_mfma_f32_16x16x32_bf16 v[22:25], v[138:141], v[220:223], v[22:25]
	v_mfma_f32_16x16x32_bf16 v[14:17], v[130:133], v[228:231], v[14:17]
	v_mfma_f32_16x16x32_bf16 v[6:9], v[138:141], v[228:231], v[6:9]
	v_mfma_f32_16x16x32_bf16 v[62:65], v[134:137], v[186:189], v[62:65]
	v_mfma_f32_16x16x32_bf16 v[54:57], v[142:145], v[186:189], v[54:57]
	v_mfma_f32_16x16x32_bf16 v[46:49], v[134:137], v[204:207], v[46:49]
	v_mfma_f32_16x16x32_bf16 v[38:41], v[142:145], v[204:207], v[38:41]
	v_mfma_f32_16x16x32_bf16 v[30:33], v[134:137], v[224:227], v[30:33]
	v_mfma_f32_16x16x32_bf16 v[22:25], v[142:145], v[224:227], v[22:25]
	v_mfma_f32_16x16x32_bf16 v[14:17], v[134:137], v[232:235], v[14:17]
	v_mfma_f32_16x16x32_bf16 v[6:9], v[142:145], v[232:235], v[6:9]
	s_setprio 0
	s_setprio 1
	v_mfma_f32_16x16x32_bf16 v[58:61], v[146:149], v[182:185], v[58:61]
	v_mfma_f32_16x16x32_bf16 v[50:53], v[174:177], v[182:185], v[50:53]
	v_mfma_f32_16x16x32_bf16 v[42:45], v[146:149], v[200:203], v[42:45]
	v_mfma_f32_16x16x32_bf16 v[34:37], v[174:177], v[200:203], v[34:37]
	v_mfma_f32_16x16x32_bf16 v[26:29], v[146:149], v[220:223], v[26:29]
	v_mfma_f32_16x16x32_bf16 v[18:21], v[174:177], v[220:223], v[18:21]
	v_mfma_f32_16x16x32_bf16 v[10:13], v[146:149], v[228:231], v[10:13]
	v_mfma_f32_16x16x32_bf16 v[2:5], v[174:177], v[228:231], v[2:5]
	v_mfma_f32_16x16x32_bf16 v[58:61], v[150:153], v[186:189], v[58:61]
	v_mfma_f32_16x16x32_bf16 v[50:53], v[178:181], v[186:189], v[50:53]
	v_mfma_f32_16x16x32_bf16 v[42:45], v[150:153], v[204:207], v[42:45]
	v_mfma_f32_16x16x32_bf16 v[34:37], v[178:181], v[204:207], v[34:37]
	v_mfma_f32_16x16x32_bf16 v[26:29], v[150:153], v[224:227], v[26:29]
	v_mfma_f32_16x16x32_bf16 v[18:21], v[178:181], v[224:227], v[18:21]
	v_mfma_f32_16x16x32_bf16 v[10:13], v[150:153], v[232:235], v[10:13]
	v_mfma_f32_16x16x32_bf16 v[2:5], v[178:181], v[232:235], v[2:5]
	s_setprio 0
	s_barrier
	s_add_i32 s41, s41, 2
	s_add_u32 s4, s4, 0x100
	s_addc_u32 s5, s5, 0
	s_add_u32 s39, s39, 0x100
	s_addc_u32 s40, s40, 0
	s_cmp_gt_u32 s41, 13
	s_cbranch_scc0 .LBB0_1446
	.p2alignl 6, 3212836864
